# hgwait + strategy 9 (loop-edge/branch-test shortening): attention fast-path branch jumps straight into the fast block, skipping the s_andn2/vccnz re-test
# speedup vs baseline: 1.0050x; 1.0001x over previous
; __device__ __forceinline__ void partialSM(f32x16& p0, f32x16& p1, float& m_reg, float& mn, float& alpha, int kt0, int qpos, int qw, int hi, const float* tb2, float cL, float cR) {
;   mn = m_reg; alpha = 1.f;
;   const int rel_hi = kt0 + 63 - qw, rel_lo = kt0 - (qw + 31);
;   if (rel_hi <= -91 || rel_lo >= 91) {
;     const float cm = ((rel_hi <= -91) ? cL : cR) - m_reg;
; #pragma unroll
;     for (int r = 0; r < 16; ++r) { p0[r] = fmaf(p0[r], C1, cm); p1[r] = fmaf(p1[r], C1, cm); }
.Lfastp_9:
	s_cmpk_lt_i32 s65, 0xffa6
	s_cselect_b32 s69, s61, s62
	v_sub_f32_e32 v80, s69, v0
	v_pk_fma_f32 v[142:143], v[126:127], s[6:7], v[80:81] op_sel_hi:[1,0,0]
	v_pk_fma_f32 v[140:141], v[124:125], s[6:7], v[80:81] op_sel_hi:[1,0,0]
	v_pk_fma_f32 v[138:139], v[122:123], s[6:7], v[80:81] op_sel_hi:[1,0,0]
	v_pk_fma_f32 v[136:137], v[120:121], s[6:7], v[80:81] op_sel_hi:[1,0,0]
	v_pk_fma_f32 v[134:135], v[118:119], s[6:7], v[80:81] op_sel_hi:[1,0,0]
	v_pk_fma_f32 v[132:133], v[116:117], s[6:7], v[80:81] op_sel_hi:[1,0,0]
	v_pk_fma_f32 v[130:131], v[114:115], s[6:7], v[80:81] op_sel_hi:[1,0,0]
	v_pk_fma_f32 v[128:129], v[112:113], s[6:7], v[80:81] op_sel_hi:[1,0,0]
	v_pk_fma_f32 v[94:95], v[110:111], s[6:7], v[80:81] op_sel_hi:[1,0,0]
	v_pk_fma_f32 v[92:93], v[108:109], s[6:7], v[80:81] op_sel_hi:[1,0,0]
	v_pk_fma_f32 v[90:91], v[106:107], s[6:7], v[80:81] op_sel_hi:[1,0,0]
	v_pk_fma_f32 v[88:89], v[104:105], s[6:7], v[80:81] op_sel_hi:[1,0,0]
	v_pk_fma_f32 v[86:87], v[102:103], s[6:7], v[80:81] op_sel_hi:[1,0,0]
	v_pk_fma_f32 v[84:85], v[100:101], s[6:7], v[80:81] op_sel_hi:[1,0,0]
	v_pk_fma_f32 v[82:83], v[98:99], s[6:7], v[80:81] op_sel_hi:[1,0,0]
	v_pk_fma_f32 v[80:81], v[96:97], s[6:7], v[80:81] op_sel_hi:[1,0,0]

; __device__ __forceinline__ void partialSM(f32x16& p0, f32x16& p1, float& m_reg, float& mn, float& alpha, int kt0, int qpos, int qw, int hi, const float* tb2, float cL, float cR) {
;   mn = m_reg; alpha = 1.f;
;   const int rel_hi = kt0 + 63 - qw, rel_lo = kt0 - (qw + 31);
;   if (rel_hi <= -91 || rel_lo >= 91) {
;     const float cm = ((rel_hi <= -91) ? cL : cR) - m_reg;
; #pragma unroll
;     for (int r = 0; r < 16; ++r) { p0[r] = fmaf(p0[r], C1, cm); p1[r] = fmaf(p1[r], C1, cm); }
.Lfastp_8:
	s_add_i32 s5, s65, 64
	s_cmpk_lt_i32 s5, 0xffa6
	s_cselect_b32 s69, s61, s62
	v_sub_f32_e32 v80, s69, v0
	v_pk_fma_f32 v[110:111], v[142:143], s[6:7], v[80:81] op_sel_hi:[1,0,0]
	v_pk_fma_f32 v[108:109], v[140:141], s[6:7], v[80:81] op_sel_hi:[1,0,0]
	v_pk_fma_f32 v[106:107], v[138:139], s[6:7], v[80:81] op_sel_hi:[1,0,0]
	v_pk_fma_f32 v[104:105], v[136:137], s[6:7], v[80:81] op_sel_hi:[1,0,0]
	v_pk_fma_f32 v[102:103], v[134:135], s[6:7], v[80:81] op_sel_hi:[1,0,0]
	v_pk_fma_f32 v[100:101], v[132:133], s[6:7], v[80:81] op_sel_hi:[1,0,0]
	v_pk_fma_f32 v[98:99], v[130:131], s[6:7], v[80:81] op_sel_hi:[1,0,0]
	v_pk_fma_f32 v[96:97], v[128:129], s[6:7], v[80:81] op_sel_hi:[1,0,0]
	v_pk_fma_f32 v[94:95], v[126:127], s[6:7], v[80:81] op_sel_hi:[1,0,0]
	v_pk_fma_f32 v[92:93], v[124:125], s[6:7], v[80:81] op_sel_hi:[1,0,0]
	v_pk_fma_f32 v[90:91], v[122:123], s[6:7], v[80:81] op_sel_hi:[1,0,0]
	v_pk_fma_f32 v[88:89], v[120:121], s[6:7], v[80:81] op_sel_hi:[1,0,0]
	v_pk_fma_f32 v[86:87], v[118:119], s[6:7], v[80:81] op_sel_hi:[1,0,0]
	v_pk_fma_f32 v[84:85], v[116:117], s[6:7], v[80:81] op_sel_hi:[1,0,0]
	v_pk_fma_f32 v[82:83], v[114:115], s[6:7], v[80:81] op_sel_hi:[1,0,0]
	v_pk_fma_f32 v[80:81], v[112:113], s[6:7], v[80:81] op_sel_hi:[1,0,0]

; __device__ __forceinline__ void partialSM(f32x16& p0, f32x16& p1, float& m_reg, float& mn, float& alpha, int kt0, int qpos, int qw, int hi, const float* tb2, float cL, float cR) {
;   mn = m_reg; alpha = 1.f;
;   const int rel_hi = kt0 + 63 - qw, rel_lo = kt0 - (qw + 31);
;   if (rel_hi <= -91 || rel_lo >= 91) {
;     const float cm = ((rel_hi <= -91) ? cL : cR) - m_reg;
; #pragma unroll
;     for (int r = 0; r < 16; ++r) { p0[r] = fmaf(p0[r], C1, cm); p1[r] = fmaf(p1[r], C1, cm); }
.Lfastp_7:
	s_addk_i32 s63, 0xf000
	s_cmpk_gt_i32 s63, 0x59
	v_mov_b32_e32 v1, s62
	v_mov_b32_e32 v66, s61
	s_cselect_b64 vcc, -1, 0
	v_cndmask_b32_e32 v1, v1, v66, vcc
	v_sub_f32_e32 v0, v1, v0
	v_pk_fma_f32 v[94:95], v[126:127], s[6:7], v[0:1] op_sel_hi:[1,0,0]
	v_pk_fma_f32 v[92:93], v[124:125], s[6:7], v[0:1] op_sel_hi:[1,0,0]
	v_pk_fma_f32 v[90:91], v[122:123], s[6:7], v[0:1] op_sel_hi:[1,0,0]
	v_pk_fma_f32 v[88:89], v[120:121], s[6:7], v[0:1] op_sel_hi:[1,0,0]
	v_pk_fma_f32 v[86:87], v[118:119], s[6:7], v[0:1] op_sel_hi:[1,0,0]
	v_pk_fma_f32 v[84:85], v[116:117], s[6:7], v[0:1] op_sel_hi:[1,0,0]
	v_pk_fma_f32 v[82:83], v[114:115], s[6:7], v[0:1] op_sel_hi:[1,0,0]
	v_pk_fma_f32 v[80:81], v[112:113], s[6:7], v[0:1] op_sel_hi:[1,0,0]
	v_pk_fma_f32 v[142:143], v[110:111], s[6:7], v[0:1] op_sel_hi:[1,0,0]
	v_pk_fma_f32 v[140:141], v[108:109], s[6:7], v[0:1] op_sel_hi:[1,0,0]
	v_pk_fma_f32 v[138:139], v[106:107], s[6:7], v[0:1] op_sel_hi:[1,0,0]
	v_pk_fma_f32 v[136:137], v[104:105], s[6:7], v[0:1] op_sel_hi:[1,0,0]
	v_pk_fma_f32 v[134:135], v[102:103], s[6:7], v[0:1] op_sel_hi:[1,0,0]
	v_pk_fma_f32 v[132:133], v[100:101], s[6:7], v[0:1] op_sel_hi:[1,0,0]
	v_pk_fma_f32 v[130:131], v[98:99], s[6:7], v[0:1] op_sel_hi:[1,0,0]
	v_pk_fma_f32 v[128:129], v[96:97], s[6:7], v[0:1] op_sel_hi:[1,0,0]

; __device__ __forceinline__ void partialSM(f32x16& p0, f32x16& p1, float& m_reg, float& mn, float& alpha, int kt0, int qpos, int qw, int hi, const float* tb2, float cL, float cR) {
;   mn = m_reg; alpha = 1.f;
;   const int rel_hi = kt0 + 63 - qw, rel_lo = kt0 - (qw + 31);
;   if (rel_hi <= -91 || rel_lo >= 91) {
;     const float cm = ((rel_hi <= -91) ? cL : cR) - m_reg;
; #pragma unroll
;     for (int r = 0; r < 16; ++r) { p0[r] = fmaf(p0[r], C1, cm); p1[r] = fmaf(p1[r], C1, cm); }
.Lfastp_6:
	s_cmpk_lt_i32 s66, 0xffa6
	s_cselect_b32 s69, s62, s63
	v_sub_f32_e32 v80, s69, v64
	v_pk_fma_f32 v[142:143], v[126:127], s[6:7], v[80:81] op_sel_hi:[1,0,0]
	v_pk_fma_f32 v[140:141], v[124:125], s[6:7], v[80:81] op_sel_hi:[1,0,0]
	v_pk_fma_f32 v[138:139], v[122:123], s[6:7], v[80:81] op_sel_hi:[1,0,0]
	v_pk_fma_f32 v[136:137], v[120:121], s[6:7], v[80:81] op_sel_hi:[1,0,0]
	v_pk_fma_f32 v[134:135], v[118:119], s[6:7], v[80:81] op_sel_hi:[1,0,0]
	v_pk_fma_f32 v[132:133], v[116:117], s[6:7], v[80:81] op_sel_hi:[1,0,0]
	v_pk_fma_f32 v[130:131], v[114:115], s[6:7], v[80:81] op_sel_hi:[1,0,0]
	v_pk_fma_f32 v[128:129], v[112:113], s[6:7], v[80:81] op_sel_hi:[1,0,0]
	v_pk_fma_f32 v[94:95], v[110:111], s[6:7], v[80:81] op_sel_hi:[1,0,0]
	v_pk_fma_f32 v[92:93], v[108:109], s[6:7], v[80:81] op_sel_hi:[1,0,0]
	v_pk_fma_f32 v[90:91], v[106:107], s[6:7], v[80:81] op_sel_hi:[1,0,0]
	v_pk_fma_f32 v[88:89], v[104:105], s[6:7], v[80:81] op_sel_hi:[1,0,0]
	v_pk_fma_f32 v[86:87], v[102:103], s[6:7], v[80:81] op_sel_hi:[1,0,0]
	v_pk_fma_f32 v[84:85], v[100:101], s[6:7], v[80:81] op_sel_hi:[1,0,0]
	v_pk_fma_f32 v[82:83], v[98:99], s[6:7], v[80:81] op_sel_hi:[1,0,0]
	v_pk_fma_f32 v[80:81], v[96:97], s[6:7], v[80:81] op_sel_hi:[1,0,0]

; __device__ __forceinline__ void partialSM(f32x16& p0, f32x16& p1, float& m_reg, float& mn, float& alpha, int kt0, int qpos, int qw, int hi, const float* tb2, float cL, float cR) {
;   mn = m_reg; alpha = 1.f;
;   const int rel_hi = kt0 + 63 - qw, rel_lo = kt0 - (qw + 31);
;   if (rel_hi <= -91 || rel_lo >= 91) {
;     const float cm = ((rel_hi <= -91) ? cL : cR) - m_reg;
; #pragma unroll
;     for (int r = 0; r < 16; ++r) { p0[r] = fmaf(p0[r], C1, cm); p1[r] = fmaf(p1[r], C1, cm); }
.Lfastp_5:
	s_add_i32 s5, s66, 64
	s_cmpk_lt_i32 s5, 0xffa6
	s_cselect_b32 s69, s62, s63
	v_sub_f32_e32 v80, s69, v64
	v_pk_fma_f32 v[110:111], v[142:143], s[6:7], v[80:81] op_sel_hi:[1,0,0]
	v_pk_fma_f32 v[108:109], v[140:141], s[6:7], v[80:81] op_sel_hi:[1,0,0]
	v_pk_fma_f32 v[106:107], v[138:139], s[6:7], v[80:81] op_sel_hi:[1,0,0]
	v_pk_fma_f32 v[104:105], v[136:137], s[6:7], v[80:81] op_sel_hi:[1,0,0]
	v_pk_fma_f32 v[102:103], v[134:135], s[6:7], v[80:81] op_sel_hi:[1,0,0]
	v_pk_fma_f32 v[100:101], v[132:133], s[6:7], v[80:81] op_sel_hi:[1,0,0]
	v_pk_fma_f32 v[98:99], v[130:131], s[6:7], v[80:81] op_sel_hi:[1,0,0]
	v_pk_fma_f32 v[96:97], v[128:129], s[6:7], v[80:81] op_sel_hi:[1,0,0]
	v_pk_fma_f32 v[94:95], v[126:127], s[6:7], v[80:81] op_sel_hi:[1,0,0]
	v_pk_fma_f32 v[92:93], v[124:125], s[6:7], v[80:81] op_sel_hi:[1,0,0]
	v_pk_fma_f32 v[90:91], v[122:123], s[6:7], v[80:81] op_sel_hi:[1,0,0]
	v_pk_fma_f32 v[88:89], v[120:121], s[6:7], v[80:81] op_sel_hi:[1,0,0]
	v_pk_fma_f32 v[86:87], v[118:119], s[6:7], v[80:81] op_sel_hi:[1,0,0]
	v_pk_fma_f32 v[84:85], v[116:117], s[6:7], v[80:81] op_sel_hi:[1,0,0]
	v_pk_fma_f32 v[82:83], v[114:115], s[6:7], v[80:81] op_sel_hi:[1,0,0]
	v_pk_fma_f32 v[80:81], v[112:113], s[6:7], v[80:81] op_sel_hi:[1,0,0]

; __device__ __forceinline__ void partialSM(f32x16& p0, f32x16& p1, float& m_reg, float& mn, float& alpha, int kt0, int qpos, int qw, int hi, const float* tb2, float cL, float cR) {
;   mn = m_reg; alpha = 1.f;
;   const int rel_hi = kt0 + 63 - qw, rel_lo = kt0 - (qw + 31);
;   if (rel_hi <= -91 || rel_lo >= 91) {
;     const float cm = ((rel_hi <= -91) ? cL : cR) - m_reg;
; #pragma unroll
;     for (int r = 0; r < 16; ++r) { p0[r] = fmaf(p0[r], C1, cm); p1[r] = fmaf(p1[r], C1, cm); }
.Lfastp_4:
	s_cmpk_lt_i32 s62, 0xffa6
	s_cselect_b32 s69, s54, s55
	v_sub_f32_e32 v128, s69, v0
	v_pk_fma_f32 v[94:95], v[126:127], s[6:7], v[128:129] op_sel_hi:[1,0,0]
	v_pk_fma_f32 v[92:93], v[124:125], s[6:7], v[128:129] op_sel_hi:[1,0,0]
	v_pk_fma_f32 v[90:91], v[122:123], s[6:7], v[128:129] op_sel_hi:[1,0,0]
	v_pk_fma_f32 v[88:89], v[120:121], s[6:7], v[128:129] op_sel_hi:[1,0,0]
	v_pk_fma_f32 v[86:87], v[118:119], s[6:7], v[128:129] op_sel_hi:[1,0,0]
	v_pk_fma_f32 v[84:85], v[116:117], s[6:7], v[128:129] op_sel_hi:[1,0,0]
	v_pk_fma_f32 v[82:83], v[114:115], s[6:7], v[128:129] op_sel_hi:[1,0,0]
	v_pk_fma_f32 v[80:81], v[112:113], s[6:7], v[128:129] op_sel_hi:[1,0,0]
	v_pk_fma_f32 v[142:143], v[110:111], s[6:7], v[128:129] op_sel_hi:[1,0,0]
	v_pk_fma_f32 v[140:141], v[108:109], s[6:7], v[128:129] op_sel_hi:[1,0,0]
	v_pk_fma_f32 v[138:139], v[106:107], s[6:7], v[128:129] op_sel_hi:[1,0,0]
	v_pk_fma_f32 v[136:137], v[104:105], s[6:7], v[128:129] op_sel_hi:[1,0,0]
	v_pk_fma_f32 v[134:135], v[102:103], s[6:7], v[128:129] op_sel_hi:[1,0,0]
	v_pk_fma_f32 v[132:133], v[100:101], s[6:7], v[128:129] op_sel_hi:[1,0,0]
	v_pk_fma_f32 v[130:131], v[98:99], s[6:7], v[128:129] op_sel_hi:[1,0,0]
	v_pk_fma_f32 v[128:129], v[96:97], s[6:7], v[128:129] op_sel_hi:[1,0,0]

; __device__ __forceinline__ void partialSM(f32x16& p0, f32x16& p1, float& m_reg, float& mn, float& alpha, int kt0, int qpos, int qw, int hi, const float* tb2, float cL, float cR) {
;   mn = m_reg; alpha = 1.f;
;   const int rel_hi = kt0 + 63 - qw, rel_lo = kt0 - (qw + 31);
;   if (rel_hi <= -91 || rel_lo >= 91) {
;     const float cm = ((rel_hi <= -91) ? cL : cR) - m_reg;
; #pragma unroll
;     for (int r = 0; r < 16; ++r) { p0[r] = fmaf(p0[r], C1, cm); p1[r] = fmaf(p1[r], C1, cm); }
.Lfastp_3:
	s_add_i32 s5, s62, 64
	s_cmpk_lt_i32 s5, 0xffa6
	s_cselect_b32 s69, s54, s55
	v_sub_f32_e32 v80, s69, v0
	v_pk_fma_f32 v[142:143], v[126:127], s[6:7], v[80:81] op_sel_hi:[1,0,0]
	v_pk_fma_f32 v[140:141], v[124:125], s[6:7], v[80:81] op_sel_hi:[1,0,0]
	v_pk_fma_f32 v[138:139], v[122:123], s[6:7], v[80:81] op_sel_hi:[1,0,0]
	v_pk_fma_f32 v[136:137], v[120:121], s[6:7], v[80:81] op_sel_hi:[1,0,0]
	v_pk_fma_f32 v[134:135], v[118:119], s[6:7], v[80:81] op_sel_hi:[1,0,0]
	v_pk_fma_f32 v[132:133], v[116:117], s[6:7], v[80:81] op_sel_hi:[1,0,0]
	v_pk_fma_f32 v[130:131], v[114:115], s[6:7], v[80:81] op_sel_hi:[1,0,0]
	v_pk_fma_f32 v[128:129], v[112:113], s[6:7], v[80:81] op_sel_hi:[1,0,0]
	v_pk_fma_f32 v[94:95], v[110:111], s[6:7], v[80:81] op_sel_hi:[1,0,0]
	v_pk_fma_f32 v[92:93], v[108:109], s[6:7], v[80:81] op_sel_hi:[1,0,0]
	v_pk_fma_f32 v[90:91], v[106:107], s[6:7], v[80:81] op_sel_hi:[1,0,0]
	v_pk_fma_f32 v[88:89], v[104:105], s[6:7], v[80:81] op_sel_hi:[1,0,0]
	v_pk_fma_f32 v[86:87], v[102:103], s[6:7], v[80:81] op_sel_hi:[1,0,0]
	v_pk_fma_f32 v[84:85], v[100:101], s[6:7], v[80:81] op_sel_hi:[1,0,0]
	v_pk_fma_f32 v[82:83], v[98:99], s[6:7], v[80:81] op_sel_hi:[1,0,0]
	v_pk_fma_f32 v[80:81], v[96:97], s[6:7], v[80:81] op_sel_hi:[1,0,0]

; __device__ __forceinline__ void partialSM(f32x16& p0, f32x16& p1, float& m_reg, float& mn, float& alpha, int kt0, int qpos, int qw, int hi, const float* tb2, float cL, float cR) {
;   mn = m_reg; alpha = 1.f;
;   const int rel_hi = kt0 + 63 - qw, rel_lo = kt0 - (qw + 31);
;   if (rel_hi <= -91 || rel_lo >= 91) {
;     const float cm = ((rel_hi <= -91) ? cL : cR) - m_reg;
; #pragma unroll
;     for (int r = 0; r < 16; ++r) { p0[r] = fmaf(p0[r], C1, cm); p1[r] = fmaf(p1[r], C1, cm); }
.Lfastp_2:
	s_addk_i32 s60, 0xf000
	s_cmpk_gt_i32 s60, 0x59
	v_mov_b32_e32 v1, s55
	v_mov_b32_e32 v66, s54
	s_cselect_b64 vcc, -1, 0
	v_cndmask_b32_e32 v1, v1, v66, vcc
	v_sub_f32_e32 v0, v1, v0
	v_pk_fma_f32 v[94:95], v[126:127], s[6:7], v[0:1] op_sel_hi:[1,0,0]
	v_pk_fma_f32 v[92:93], v[124:125], s[6:7], v[0:1] op_sel_hi:[1,0,0]
	v_pk_fma_f32 v[90:91], v[122:123], s[6:7], v[0:1] op_sel_hi:[1,0,0]
	v_pk_fma_f32 v[88:89], v[120:121], s[6:7], v[0:1] op_sel_hi:[1,0,0]
	v_pk_fma_f32 v[86:87], v[118:119], s[6:7], v[0:1] op_sel_hi:[1,0,0]
	v_pk_fma_f32 v[84:85], v[116:117], s[6:7], v[0:1] op_sel_hi:[1,0,0]
	v_pk_fma_f32 v[82:83], v[114:115], s[6:7], v[0:1] op_sel_hi:[1,0,0]
	v_pk_fma_f32 v[80:81], v[112:113], s[6:7], v[0:1] op_sel_hi:[1,0,0]
	v_pk_fma_f32 v[142:143], v[110:111], s[6:7], v[0:1] op_sel_hi:[1,0,0]
	v_pk_fma_f32 v[140:141], v[108:109], s[6:7], v[0:1] op_sel_hi:[1,0,0]
	v_pk_fma_f32 v[138:139], v[106:107], s[6:7], v[0:1] op_sel_hi:[1,0,0]
	v_pk_fma_f32 v[136:137], v[104:105], s[6:7], v[0:1] op_sel_hi:[1,0,0]
	v_pk_fma_f32 v[134:135], v[102:103], s[6:7], v[0:1] op_sel_hi:[1,0,0]
	v_pk_fma_f32 v[132:133], v[100:101], s[6:7], v[0:1] op_sel_hi:[1,0,0]
	v_pk_fma_f32 v[130:131], v[98:99], s[6:7], v[0:1] op_sel_hi:[1,0,0]
	v_pk_fma_f32 v[128:129], v[96:97], s[6:7], v[0:1] op_sel_hi:[1,0,0]

; __device__ __forceinline__ void partialSM(f32x16& p0, f32x16& p1, float& m_reg, float& mn, float& alpha, int kt0, int qpos, int qw, int hi, const float* tb2, float cL, float cR) {
;   mn = m_reg; alpha = 1.f;
;   const int rel_hi = kt0 + 63 - qw, rel_lo = kt0 - (qw + 31);
;   if (rel_hi <= -91 || rel_lo >= 91) {
;     const float cm = ((rel_hi <= -91) ? cL : cR) - m_reg;
; #pragma unroll
;     for (int r = 0; r < 16; ++r) { p0[r] = fmaf(p0[r], C1, cm); p1[r] = fmaf(p1[r], C1, cm); }
.Lfastp_1:
	s_cmpk_lt_i32 s48, 0xffa6
	s_cselect_b32 s69, s52, s53
	v_sub_f32_e32 v128, s69, v64
	v_pk_fma_f32 v[94:95], v[126:127], s[6:7], v[128:129] op_sel_hi:[1,0,0]
	v_pk_fma_f32 v[92:93], v[124:125], s[6:7], v[128:129] op_sel_hi:[1,0,0]
	v_pk_fma_f32 v[90:91], v[122:123], s[6:7], v[128:129] op_sel_hi:[1,0,0]
	v_pk_fma_f32 v[88:89], v[120:121], s[6:7], v[128:129] op_sel_hi:[1,0,0]
	v_pk_fma_f32 v[86:87], v[118:119], s[6:7], v[128:129] op_sel_hi:[1,0,0]
	v_pk_fma_f32 v[84:85], v[116:117], s[6:7], v[128:129] op_sel_hi:[1,0,0]
	v_pk_fma_f32 v[82:83], v[114:115], s[6:7], v[128:129] op_sel_hi:[1,0,0]
	v_pk_fma_f32 v[80:81], v[112:113], s[6:7], v[128:129] op_sel_hi:[1,0,0]
	v_pk_fma_f32 v[142:143], v[110:111], s[6:7], v[128:129] op_sel_hi:[1,0,0]
	v_pk_fma_f32 v[140:141], v[108:109], s[6:7], v[128:129] op_sel_hi:[1,0,0]
	v_pk_fma_f32 v[138:139], v[106:107], s[6:7], v[128:129] op_sel_hi:[1,0,0]
	v_pk_fma_f32 v[136:137], v[104:105], s[6:7], v[128:129] op_sel_hi:[1,0,0]
	v_pk_fma_f32 v[134:135], v[102:103], s[6:7], v[128:129] op_sel_hi:[1,0,0]
	v_pk_fma_f32 v[132:133], v[100:101], s[6:7], v[128:129] op_sel_hi:[1,0,0]
	v_pk_fma_f32 v[130:131], v[98:99], s[6:7], v[128:129] op_sel_hi:[1,0,0]
	v_pk_fma_f32 v[128:129], v[96:97], s[6:7], v[128:129] op_sel_hi:[1,0,0]

; __device__ __forceinline__ void partialSM(f32x16& p0, f32x16& p1, float& m_reg, float& mn, float& alpha, int kt0, int qpos, int qw, int hi, const float* tb2, float cL, float cR) {
;   mn = m_reg; alpha = 1.f;
;   const int rel_hi = kt0 + 63 - qw, rel_lo = kt0 - (qw + 31);
;   if (rel_hi <= -91 || rel_lo >= 91) {
;     const float cm = ((rel_hi <= -91) ? cL : cR) - m_reg;
; #pragma unroll
;     for (int r = 0; r < 16; ++r) { p0[r] = fmaf(p0[r], C1, cm); p1[r] = fmaf(p1[r], C1, cm); }
.Lfastp_0:
	s_addk_i32 s39, 0xf000
	s_cmpk_gt_i32 s39, 0x59
	v_mov_b32_e32 v65, s53
	v_mov_b32_e32 v66, s52
	s_cselect_b64 vcc, -1, 0
	v_cndmask_b32_e32 v65, v65, v66, vcc
	v_sub_f32_e32 v64, v65, v64
	v_pk_fma_f32 v[94:95], v[126:127], s[6:7], v[64:65] op_sel_hi:[1,0,0]
	v_pk_fma_f32 v[92:93], v[124:125], s[6:7], v[64:65] op_sel_hi:[1,0,0]
	v_pk_fma_f32 v[90:91], v[122:123], s[6:7], v[64:65] op_sel_hi:[1,0,0]
	v_pk_fma_f32 v[88:89], v[120:121], s[6:7], v[64:65] op_sel_hi:[1,0,0]
	v_pk_fma_f32 v[86:87], v[118:119], s[6:7], v[64:65] op_sel_hi:[1,0,0]
	v_pk_fma_f32 v[84:85], v[116:117], s[6:7], v[64:65] op_sel_hi:[1,0,0]
	v_pk_fma_f32 v[82:83], v[114:115], s[6:7], v[64:65] op_sel_hi:[1,0,0]
	v_pk_fma_f32 v[80:81], v[112:113], s[6:7], v[64:65] op_sel_hi:[1,0,0]
	v_pk_fma_f32 v[142:143], v[110:111], s[6:7], v[64:65] op_sel_hi:[1,0,0]
	v_pk_fma_f32 v[140:141], v[108:109], s[6:7], v[64:65] op_sel_hi:[1,0,0]
	v_pk_fma_f32 v[138:139], v[106:107], s[6:7], v[64:65] op_sel_hi:[1,0,0]
	v_pk_fma_f32 v[136:137], v[104:105], s[6:7], v[64:65] op_sel_hi:[1,0,0]
	v_pk_fma_f32 v[134:135], v[102:103], s[6:7], v[64:65] op_sel_hi:[1,0,0]
	v_pk_fma_f32 v[132:133], v[100:101], s[6:7], v[64:65] op_sel_hi:[1,0,0]
	v_pk_fma_f32 v[130:131], v[98:99], s[6:7], v[64:65] op_sel_hi:[1,0,0]
	v_pk_fma_f32 v[128:129], v[96:97], s[6:7], v[64:65] op_sel_hi:[1,0,0]
